# plus P7 headnorm: 7 serialized o-gate loads per row hoisted; P8 merge GEMM mid-hook: gate loads hoisted in a ring of 8 groups with counted vmcnt
# speedup vs baseline: 1.0263x; 1.0139x over previous
; #define GAS __attribute__((address_space(1)))
; __device__ __forceinline__ unsigned pk2(float lo, float hi) { return f2bf(lo) | (f2bf(hi) << 16); }
; __device__ __forceinline__ float bflo(unsigned w) { return __uint_as_float(w << 16); }
; __device__ __forceinline__ float bfhi(unsigned w) { return __uint_as_float(w & 0xffff0000u); }
; __device__ __forceinline__ float dot4(f32x4 a, f32x4 b) { return (a[0] * b[0] + a[1] * b[1]) + (a[2] * b[2] + a[3] * b[3]); }
; __device__ __forceinline__ void headnorm_all(Frame& F, const Args& a) {
;     ...
;     for (int r = gw; r < M; r += NGW) {
;         const GAS v2u* hp = (const GAS v2u*)(HRAW + (size_t)r * D) + lane; f32x4 v[8]; float ss[4];
;         f32x4 di;
; #pragma unroll
;         for (int hh = 0; hh < 4; ++hh) { const f32x4 x = *(const GAS f32x4*)(WSP(float, WS_DENINV) + ((size_t)r * 4 + hh) * 4); di[hh] = 1.0f / fmaxf(fabsf(x[0] + x[2]), x[1]); }
; #pragma unroll
;         for (int j = 0; j < 8; ++j) { const v2u hw = hp[64 * j]; v[j] = (f32x4){bflo(hw.x), bfhi(hw.x), bflo(hw.y), bfhi(hw.y)} * di[j >> 1]; }
; #pragma unroll
;         for (int hh = 0; hh < 4; ++hh) { ss[hh] = wave_sum(dot4(v[2 * hh], v[2 * hh]) + dot4(v[2 * hh + 1], v[2 * hh + 1])); ss[hh] = 1.0f / sqrtf(ss[hh] * (1.0f / 512.0f) + EPS); }
; #pragma unroll
;         for (int j = 0; j < 8; ++j) { const f32x4 g = gh[j]; const v2u ow = ((const GAS v2u*)(Z2 + (size_t)r * D))[lane + 64 * j];
;             const f32x4 o = (f32x4){bflo(ow.x), bfhi(ow.x), bflo(ow.y), bfhi(ow.y)}; const f32x4 y = (v[j] * ss[j >> 1]) * g * o;
;             v2u w; w.x = pk2(y[0], y[1]); w.y = pk2(y[2], y[3]); ((GAS v2u*)(HA + (size_t)r * (2 * D)))[lane + 64 * j] = w; }
.LBB0_1136:
	v_lshl_add_u64 v[38:39], s[34:35], 0, v[36:37]
	v_add_co_u32_e32 v44, vcc, s3, v38
	v_lshl_add_u64 v[42:43], s[34:35], 0, v[34:35]
	s_nop 0
	v_addc_co_u32_e32 v45, vcc, 0, v39, vcc
	v_add_co_u32_e32 v40, vcc, s22, v38
	s_add_u32 s0, s34, s16
	s_nop 0
	v_addc_co_u32_e32 v41, vcc, 0, v39, vcc
	v_add_co_u32_e32 v38, vcc, s24, v42
	s_addc_u32 s1, s35, s17
	s_nop 0
	v_addc_co_u32_e32 v39, vcc, 0, v43, vcc
	global_load_dwordx2 v[46:47], v[44:45], off
	global_load_dwordx2 v[48:49], v[44:45], off offset:512
	global_load_dwordx2 v[76:77], v[44:45], off offset:1024
	global_load_dwordx2 v[78:79], v[44:45], off offset:1536
	global_load_dwordx2 v[80:81], v[44:45], off offset:2048
	global_load_dwordx2 v[82:83], v[44:45], off offset:2560
	global_load_dwordx2 v[84:85], v[44:45], off offset:3072
	global_load_dwordx2 v[42:43], v[44:45], off offset:3584
	global_load_dwordx2 v[86:87], v[40:41], off
	global_load_dwordx2 v[112:113], v[40:41], off offset:512
	global_load_dwordx2 v[114:115], v[40:41], off offset:1024
	global_load_dwordx2 v[116:117], v[40:41], off offset:1536
	global_load_dwordx2 v[118:119], v[40:41], off offset:2048
	global_load_dwordx2 v[120:121], v[40:41], off offset:2560
	global_load_dwordx2 v[122:123], v[40:41], off offset:3072
	global_load_dwordx2 v[124:125], v[40:41], off offset:3584
	s_add_u32 s6, s0, 0x3d000000
	s_addc_u32 s7, s1, 0
	global_load_dwordx4 v[50:53], v69, s[0:1]
	global_load_dwordx4 v[54:57], v68, s[6:7] offset:16
	global_load_dwordx4 v[58:61], v68, s[6:7] offset:32
	global_load_dwordx4 v[72:75], v68, s[6:7] offset:48
	s_add_i32 s10, s10, s12
	s_add_u32 s16, s16, s18
	s_addc_u32 s17, s17, s19
	v_lshl_add_u64 v[34:35], v[34:35], 0, s[14:15]
	v_lshl_add_u64 v[36:37], v[36:37], 0, s[20:21]
	s_cmpk_lt_i32 s10, 0x2200
	s_waitcnt vmcnt(0)
	v_lshlrev_b32_e32 v88, 16, v46
	v_and_b32_e32 v89, 0xffff0000, v46
	v_lshlrev_b32_e32 v90, 16, v47
	v_and_b32_e32 v91, 0xffff0000, v47
	v_lshlrev_b32_e32 v92, 16, v48
	v_and_b32_e32 v93, 0xffff0000, v48
	v_lshlrev_b32_e32 v94, 16, v49
	v_lshlrev_b32_e32 v46, 16, v42
	v_and_b32_e32 v47, 0xffff0000, v42
	v_add_f32_e32 v42, v50, v52
	v_max_f32_e32 v50, v51, v51
	v_add_f32_e32 v51, v54, v56
	v_max_f32_e32 v52, v55, v55
	v_max_f32_e64 v42, |v42|, v50
	v_add_f32_e32 v53, v58, v60
	v_max_f32_e32 v54, v59, v59
	v_max_f32_e64 v50, |v51|, v52
	v_div_scale_f32 v52, s[0:1], v42, v42, 1.0
	v_add_f32_e32 v55, v72, v74
	v_max_f32_e32 v56, v73, v73
	v_max_f32_e64 v51, |v53|, v54
	v_div_scale_f32 v54, s[0:1], v50, v50, 1.0
	v_rcp_f32_e32 v60, v52
	v_max_f32_e64 v108, |v55|, v56
	v_div_scale_f32 v56, s[6:7], v51, v51, 1.0
	v_rcp_f32_e32 v61, v54
	v_rcp_f32_e32 v72, v56
	v_div_scale_f32 v58, s[8:9], v108, v108, 1.0
	v_rcp_f32_e32 v104, v58
	v_fma_f32 v73, -v52, v60, 1.0
	v_div_scale_f32 v53, vcc, 1.0, v42, 1.0
	v_fma_f32 v74, -v54, v61, 1.0
	v_fmac_f32_e32 v60, v73, v60
	v_div_scale_f32 v55, s[0:1], 1.0, v50, 1.0
	v_fma_f32 v75, -v56, v72, 1.0
	v_fmac_f32_e32 v61, v74, v61
	v_mul_f32_e32 v73, v53, v60
	v_div_scale_f32 v57, s[6:7], 1.0, v51, 1.0
	v_fmac_f32_e32 v72, v75, v72
	v_mul_f32_e32 v74, v55, v61
	v_fma_f32 v106, -v52, v73, v53
	v_fma_f32 v105, -v58, v104, 1.0
	v_mul_f32_e32 v75, v57, v72
	v_fma_f32 v107, -v54, v74, v55
	v_fmac_f32_e32 v73, v106, v60
	v_div_scale_f32 v59, s[8:9], 1.0, v108, 1.0
	v_fmac_f32_e32 v104, v105, v104
	v_fma_f32 v109, -v56, v75, v57
	v_fmac_f32_e32 v74, v107, v61
	v_fma_f32 v52, -v52, v73, v53
	v_mul_f32_e32 v105, v59, v104
	v_fmac_f32_e32 v75, v109, v72
	v_fma_f32 v53, -v54, v74, v55
	v_div_fmas_f32 v52, v52, v60, v73
	s_mov_b64 vcc, s[0:1]
	v_and_b32_e32 v95, 0xffff0000, v49
	v_fma_f32 v110, -v58, v105, v59
	v_fma_f32 v54, -v56, v75, v57
	v_div_fixup_f32 v42, v52, v42, 1.0
	v_div_fmas_f32 v52, v53, v61, v74
	s_mov_b64 vcc, s[6:7]
	v_lshlrev_b32_e32 v98, 16, v78
	v_and_b32_e32 v99, 0xffff0000, v78
	v_fmac_f32_e32 v105, v110, v104
	v_div_fixup_f32 v50, v52, v50, 1.0
	v_div_fmas_f32 v52, v54, v72, v75
	v_pk_mul_f32 v[72:73], v[42:43], v[90:91] op_sel_hi:[0,1]
	v_pk_mul_f32 v[74:75], v[42:43], v[88:89] op_sel_hi:[0,1]
	v_pk_mul_f32 v[88:89], v[42:43], v[94:95] op_sel_hi:[0,1]
	v_pk_mul_f32 v[90:91], v[42:43], v[92:93] op_sel_hi:[0,1]
	v_lshlrev_b32_e32 v96, 16, v76
	v_and_b32_e32 v97, 0xffff0000, v76
	v_lshlrev_b32_e32 v76, 16, v77
	v_and_b32_e32 v77, 0xffff0000, v77
	v_lshlrev_b32_e32 v78, 16, v79
	v_and_b32_e32 v79, 0xffff0000, v79
	v_lshlrev_b32_e32 v100, 16, v80
	v_and_b32_e32 v101, 0xffff0000, v80
	v_lshlrev_b32_e32 v80, 16, v81
	v_and_b32_e32 v81, 0xffff0000, v81
	v_lshlrev_b32_e32 v102, 16, v82
	v_and_b32_e32 v103, 0xffff0000, v82
	v_lshlrev_b32_e32 v82, 16, v83
	v_and_b32_e32 v83, 0xffff0000, v83
	v_fma_f32 v55, -v58, v105, v59
	v_div_fixup_f32 v42, v52, v51, 1.0
	s_mov_b64 vcc, s[8:9]
	v_pk_mul_f32 v[60:61], v[50:51], v[98:99] op_sel_hi:[0,1]
	v_mov_b32_e32 v94, v75
	v_mov_b32_e32 v95, v91
	v_mov_b32_e32 v98, v73
	v_mov_b32_e32 v99, v89
	v_div_fmas_f32 v109, v55, v104, v105
	v_pk_mul_f32 v[76:77], v[50:51], v[76:77] op_sel_hi:[0,1]
	v_pk_mul_f32 v[92:93], v[50:51], v[96:97] op_sel_hi:[0,1]
	v_pk_mul_f32 v[58:59], v[50:51], v[78:79] op_sel_hi:[0,1]
	v_mov_b32_e32 v78, v74
	v_mov_b32_e32 v79, v90
	v_mov_b32_e32 v96, v72
	v_mov_b32_e32 v97, v88
	v_pk_mul_f32 v[54:55], v[42:43], v[80:81] op_sel_hi:[0,1]
	v_pk_mul_f32 v[50:51], v[42:43], v[82:83] op_sel_hi:[0,1]
	v_pk_mul_f32 v[80:81], v[94:95], v[94:95]
	v_pk_mul_f32 v[82:83], v[98:99], v[98:99]
	v_pk_mul_f32 v[56:57], v[42:43], v[100:101] op_sel_hi:[0,1]
	v_pk_mul_f32 v[52:53], v[42:43], v[102:103] op_sel_hi:[0,1]
	v_mov_b32_e32 v98, v93
	v_mov_b32_e32 v99, v61
	v_mov_b32_e32 v102, v77
	v_mov_b32_e32 v103, v59
	v_pk_fma_f32 v[78:79], v[78:79], v[78:79], v[80:81]
	v_pk_fma_f32 v[80:81], v[96:97], v[96:97], v[82:83]
	v_mov_b32_e32 v94, v92
	v_mov_b32_e32 v95, v60
	v_mov_b32_e32 v100, v76
	v_mov_b32_e32 v101, v58
	v_pk_mul_f32 v[82:83], v[98:99], v[98:99]
	v_pk_mul_f32 v[96:97], v[102:103], v[102:103]
	v_mov_b32_e32 v102, v57
	v_mov_b32_e32 v103, v53
	v_pk_add_f32 v[78:79], v[78:79], v[80:81]
	v_mov_b32_e32 v98, v56
	v_mov_b32_e32 v99, v52
	v_mov_b32_e32 v106, v55
	v_mov_b32_e32 v107, v51
	v_pk_fma_f32 v[80:81], v[94:95], v[94:95], v[82:83]
	v_pk_fma_f32 v[82:83], v[100:101], v[100:101], v[96:97]
	v_pk_mul_f32 v[94:95], v[102:103], v[102:103]
	v_add_f32_e32 v42, v78, v79
	v_mov_b32_e32 v104, v54
	v_mov_b32_e32 v105, v50
	v_pk_mul_f32 v[96:97], v[106:107], v[106:107]
	v_pk_add_f32 v[78:79], v[80:81], v[82:83]
	v_pk_fma_f32 v[80:81], v[98:99], v[98:99], v[94:95]
	ds_bpermute_b32 v94, v62, v42
	v_pk_fma_f32 v[82:83], v[104:105], v[104:105], v[96:97]
	v_add_f32_e32 v95, v78, v79
	v_pk_add_f32 v[78:79], v[80:81], v[82:83]
	ds_bpermute_b32 v80, v62, v95
	s_waitcnt lgkmcnt(1)
; #define GAS __attribute__((address_space(1)))
; __device__ __forceinline__ unsigned pk2(float lo, float hi) { return f2bf(lo) | (f2bf(hi) << 16); }
; __device__ __forceinline__ float bflo(unsigned w) { return __uint_as_float(w << 16); }
; __device__ __forceinline__ float bfhi(unsigned w) { return __uint_as_float(w & 0xffff0000u); }
; __device__ __forceinline__ float dot4(f32x4 a, f32x4 b) { return (a[0] * b[0] + a[1] * b[1]) + (a[2] * b[2] + a[3] * b[3]); }
; __device__ __forceinline__ void headnorm_all(Frame& F, const Args& a) {
;     ...
;     for (int r = gw; r < M; r += NGW) {
;         const GAS v2u* hp = (const GAS v2u*)(HRAW + (size_t)r * D) + lane; f32x4 v[8]; float ss[4];
;         f32x4 di;
; #pragma unroll
;         for (int hh = 0; hh < 4; ++hh) { const f32x4 x = *(const GAS f32x4*)(WSP(float, WS_DENINV) + ((size_t)r * 4 + hh) * 4); di[hh] = 1.0f / fmaxf(fabsf(x[0] + x[2]), x[1]); }
; #pragma unroll
;         for (int j = 0; j < 8; ++j) { const v2u hw = hp[64 * j]; v[j] = (f32x4){bflo(hw.x), bfhi(hw.x), bflo(hw.y), bfhi(hw.y)} * di[j >> 1]; }
; #pragma unroll
;         for (int hh = 0; hh < 4; ++hh) { ss[hh] = wave_sum(dot4(v[2 * hh], v[2 * hh]) + dot4(v[2 * hh + 1], v[2 * hh + 1])); ss[hh] = 1.0f / sqrtf(ss[hh] * (1.0f / 512.0f) + EPS); }
; #pragma unroll
;         for (int j = 0; j < 8; ++j) { const f32x4 g = gh[j]; const v2u ow = ((const GAS v2u*)(Z2 + (size_t)r * D))[lane + 64 * j];
;             const f32x4 o = (f32x4){bflo(ow.x), bfhi(ow.x), bflo(ow.y), bfhi(ow.y)}; const f32x4 y = (v[j] * ss[j >> 1]) * g * o;
;             v2u w; w.x = pk2(y[0], y[1]); w.y = pk2(y[2], y[3]); ((GAS v2u*)(HA + (size_t)r * (2 * D)))[lane + 64 * j] = w; }
	v_add_f32_e32 v42, v42, v94
	ds_bpermute_b32 v81, v63, v42
	v_add_f32_e32 v78, v78, v79
	ds_bpermute_b32 v79, v62, v78
	s_waitcnt lgkmcnt(2)
	v_add_f32_e32 v80, v95, v80
	ds_bpermute_b32 v82, v63, v80
	s_waitcnt lgkmcnt(2)
	v_add_f32_e32 v42, v42, v81
	ds_bpermute_b32 v81, v64, v42
	s_waitcnt lgkmcnt(2)
	v_add_f32_e32 v78, v78, v79
	ds_bpermute_b32 v79, v63, v78
	s_waitcnt lgkmcnt(2)
	v_add_f32_e32 v80, v80, v82
	ds_bpermute_b32 v82, v64, v80
	s_waitcnt lgkmcnt(2)
	v_add_f32_e32 v42, v42, v81
	ds_bpermute_b32 v81, v65, v42
	s_waitcnt lgkmcnt(2)
	v_add_f32_e32 v78, v78, v79
	ds_bpermute_b32 v79, v64, v78
	s_waitcnt lgkmcnt(2)
	v_add_f32_e32 v80, v80, v82
	ds_bpermute_b32 v82, v65, v80
	s_waitcnt lgkmcnt(2)
	v_add_f32_e32 v42, v42, v81
	ds_bpermute_b32 v81, v66, v42
	s_waitcnt lgkmcnt(2)
	v_add_f32_e32 v78, v78, v79
	ds_bpermute_b32 v79, v65, v78
	s_waitcnt lgkmcnt(2)
	v_add_f32_e32 v80, v80, v82
	ds_bpermute_b32 v82, v66, v80
	s_waitcnt lgkmcnt(2)
	v_add_f32_e32 v42, v42, v81
	ds_bpermute_b32 v81, v67, v42
	s_waitcnt lgkmcnt(2)
	v_add_f32_e32 v78, v78, v79
	ds_bpermute_b32 v79, v66, v78
	s_waitcnt lgkmcnt(2)
	v_add_f32_e32 v80, v80, v82
	ds_bpermute_b32 v82, v67, v80
	s_waitcnt lgkmcnt(2)
	v_add_f32_e32 v42, v42, v81
	v_fmamk_f32 v42, v42, 0x3b000000, v70
	s_waitcnt lgkmcnt(1)
	v_add_f32_e32 v83, v78, v79
	v_mul_f32_e32 v79, 0x4f800000, v42
	s_waitcnt lgkmcnt(0)
	v_add_f32_e32 v78, v80, v82
	v_cmp_gt_f32_e32 vcc, s13, v42
	v_fmamk_f32 v78, v78, 0x3b000000, v70
	v_cmp_gt_f32_e64 s[0:1], s13, v78
	v_cndmask_b32_e32 v42, v42, v79, vcc
	v_mul_f32_e32 v79, 0x4f800000, v78
	v_sqrt_f32_e32 v80, v42
	v_cndmask_b32_e64 v78, v78, v79, s[0:1]
	v_sqrt_f32_e32 v79, v78
	v_lshlrev_b32_e32 v44, 16, v84
	v_add_u32_e32 v81, -1, v80
	v_add_u32_e32 v82, 1, v80
	v_fma_f32 v94, -v81, v80, v42
	v_fma_f32 v95, -v82, v80, v42
	v_add_u32_e32 v96, -1, v79
	v_cmp_ge_f32_e64 s[6:7], 0, v94
	v_add_u32_e32 v97, 1, v79
	v_fma_f32 v94, -v97, v79, v78
	v_cndmask_b32_e64 v80, v80, v81, s[6:7]
	v_fma_f32 v81, -v96, v79, v78
	v_cmp_lt_f32_e64 s[6:7], 0, v95
	v_and_b32_e32 v45, 0xffff0000, v84
	v_lshlrev_b32_e32 v48, 16, v85
	v_cndmask_b32_e64 v80, v80, v82, s[6:7]
	v_cmp_ge_f32_e64 s[6:7], 0, v81
	v_mul_f32_e32 v81, 0x37800000, v80
	v_cndmask_b32_e32 v80, v80, v81, vcc
	v_cndmask_b32_e64 v79, v79, v96, s[6:7]
	v_cmp_lt_f32_e64 s[6:7], 0, v94
	v_cmp_class_f32_e32 vcc, v42, v71
	v_and_b32_e32 v49, 0xffff0000, v85
	v_cndmask_b32_e64 v79, v79, v97, s[6:7]
	v_mul_f32_e32 v81, 0x37800000, v79
	v_cndmask_b32_e32 v42, v80, v42, vcc
	v_cndmask_b32_e64 v79, v79, v81, s[0:1]
	v_cmp_class_f32_e32 vcc, v78, v71
	v_div_scale_f32 v80, s[0:1], v42, v42, 1.0
	s_nop 0
	v_cndmask_b32_e32 v82, v79, v78, vcc
	v_rcp_f32_e32 v78, v80
	v_div_scale_f32 v79, s[6:7], v82, v82, 1.0
	v_rcp_f32_e32 v95, v79
	v_fma_f32 v96, -v80, v78, 1.0
	v_div_scale_f32 v81, s[0:1], 1.0, v42, 1.0
	v_fmac_f32_e32 v78, v96, v78
	v_fma_f32 v96, -v79, v95, 1.0
	v_mul_f32_e32 v97, v81, v78
	v_fmac_f32_e32 v95, v96, v95
	v_fma_f32 v96, -v80, v97, v81
	v_fmac_f32_e32 v97, v96, v78
	v_fma_f32 v80, -v80, v97, v81
	s_mov_b64 vcc, s[0:1]
	v_div_fmas_f32 v78, v80, v78, v97
	v_div_scale_f32 v94, s[6:7], 1.0, v82, 1.0
	v_div_fixup_f32 v42, v78, v42, 1.0
	v_mul_f32_e32 v98, v94, v95
	v_pk_mul_f32 v[72:73], v[72:73], v[42:43] op_sel_hi:[1,0]
	v_pk_mul_f32 v[74:75], v[74:75], v[42:43] op_sel_hi:[1,0]
	v_lshlrev_b32_e32 v84, 16, v86
	v_and_b32_e32 v85, 0xffff0000, v86
	v_lshlrev_b32_e32 v86, 16, v87
	v_and_b32_e32 v87, 0xffff0000, v87
	v_fma_f32 v96, -v79, v98, v94
	v_pk_mul_f32 v[74:75], v[2:3], v[74:75]
	v_pk_mul_f32 v[72:73], v[4:5], v[72:73]
	v_fmac_f32_e32 v98, v96, v95
	v_pk_mul_f32 v[72:73], v[72:73], v[86:87]
	v_pk_mul_f32 v[74:75], v[74:75], v[84:85]
	v_fma_f32 v94, -v79, v98, v94
	v_pk_mul_f32 v[78:79], v[88:89], v[42:43] op_sel_hi:[1,0]
	v_pk_mul_f32 v[80:81], v[90:91], v[42:43] op_sel_hi:[1,0]
	v_bfe_u32 v42, v74, 16, 1
	v_bfe_u32 v85, v72, 16, 1
	v_bfe_u32 v84, v75, 16, 1
	v_bfe_u32 v86, v73, 16, 1
	v_add3_u32 v42, v74, v42, s23
	v_add3_u32 v72, v72, v85, s23
	v_add3_u32 v74, v75, v84, s23
	v_add3_u32 v73, v73, v86, s23
	v_lshrrev_b32_e32 v42, 16, v42
	v_lshrrev_b32_e32 v75, 16, v72
	v_and_or_b32 v72, v74, s11, v42
	v_and_or_b32 v73, v73, s11, v75
	global_store_dwordx2 v[38:39], v[72:73], off
	v_pk_mul_f32 v[80:81], v[6:7], v[80:81]
	v_pk_mul_f32 v[78:79], v[8:9], v[78:79]
	s_mov_b64 vcc, s[6:7]
	v_lshlrev_b32_e32 v74, 16, v112
	v_and_b32_e32 v75, 0xffff0000, v112
	v_lshlrev_b32_e32 v72, 16, v113
	v_and_b32_e32 v73, 0xffff0000, v113
	v_pk_mul_f32 v[72:73], v[78:79], v[72:73]
	v_pk_mul_f32 v[74:75], v[80:81], v[74:75]
	v_bfe_u32 v79, v72, 16, 1
	v_bfe_u32 v42, v74, 16, 1
	v_bfe_u32 v78, v75, 16, 1
	v_bfe_u32 v80, v73, 16, 1
	v_add3_u32 v42, v74, v42, s23
	v_add3_u32 v72, v72, v79, s23
	v_add3_u32 v74, v75, v78, s23
	v_add3_u32 v73, v73, v80, s23
	v_lshrrev_b32_e32 v42, 16, v42
	v_lshrrev_b32_e32 v75, 16, v72
	v_and_or_b32 v72, v74, s11, v42
	v_and_or_b32 v73, v73, s11, v75
	global_store_dwordx2 v[38:39], v[72:73], off offset:512
	v_div_fmas_f32 v42, v94, v95, v98
	v_div_fixup_f32 v42, v42, v82, 1.0
	v_pk_mul_f32 v[74:75], v[76:77], v[42:43] op_sel_hi:[1,0]
	v_pk_mul_f32 v[76:77], v[92:93], v[42:43] op_sel_hi:[1,0]
	v_pk_mul_f32 v[74:75], v[12:13], v[74:75]
	v_pk_mul_f32 v[76:77], v[10:11], v[76:77]
	v_pk_mul_f32 v[58:59], v[58:59], v[42:43] op_sel_hi:[1,0]
	v_pk_mul_f32 v[60:61], v[60:61], v[42:43] op_sel_hi:[1,0]
	v_pk_mul_f32 v[58:59], v[16:17], v[58:59]
	v_pk_mul_f32 v[60:61], v[14:15], v[60:61]
	v_lshlrev_b32_e32 v78, 16, v114
	v_and_b32_e32 v79, 0xffff0000, v114
	v_lshlrev_b32_e32 v72, 16, v115
	v_and_b32_e32 v73, 0xffff0000, v115
	v_pk_mul_f32 v[72:73], v[74:75], v[72:73]
	v_pk_mul_f32 v[74:75], v[76:77], v[78:79]
	v_bfe_u32 v78, v72, 16, 1
	v_bfe_u32 v76, v74, 16, 1
	v_bfe_u32 v77, v75, 16, 1
	v_bfe_u32 v79, v73, 16, 1
	v_add3_u32 v74, v74, v76, s23
	v_add3_u32 v72, v72, v78, s23
	v_add3_u32 v75, v75, v77, s23
	v_add3_u32 v73, v73, v79, s23
	v_lshrrev_b32_e32 v74, 16, v74
	v_lshrrev_b32_e32 v76, 16, v72
	v_and_or_b32 v72, v75, s11, v74
	v_and_or_b32 v73, v73, s11, v76
	global_store_dwordx2 v[38:39], v[72:73], off offset:1024
	ds_bpermute_b32 v74, v67, v83
	s_waitcnt lgkmcnt(0)
; #define GAS __attribute__((address_space(1)))
; __device__ __forceinline__ unsigned pk2(float lo, float hi) { return f2bf(lo) | (f2bf(hi) << 16); }
; __device__ __forceinline__ float bflo(unsigned w) { return __uint_as_float(w << 16); }
; __device__ __forceinline__ float bfhi(unsigned w) { return __uint_as_float(w & 0xffff0000u); }
; __device__ __forceinline__ float dot4(f32x4 a, f32x4 b) { return (a[0] * b[0] + a[1] * b[1]) + (a[2] * b[2] + a[3] * b[3]); }
; __device__ __forceinline__ void headnorm_all(Frame& F, const Args& a) {
;     ...
;     for (int r = gw; r < M; r += NGW) {
;         const GAS v2u* hp = (const GAS v2u*)(HRAW + (size_t)r * D) + lane; f32x4 v[8]; float ss[4];
;         f32x4 di;
; #pragma unroll
;         for (int hh = 0; hh < 4; ++hh) { const f32x4 x = *(const GAS f32x4*)(WSP(float, WS_DENINV) + ((size_t)r * 4 + hh) * 4); di[hh] = 1.0f / fmaxf(fabsf(x[0] + x[2]), x[1]); }
; #pragma unroll
;         for (int j = 0; j < 8; ++j) { const v2u hw = hp[64 * j]; v[j] = (f32x4){bflo(hw.x), bfhi(hw.x), bflo(hw.y), bfhi(hw.y)} * di[j >> 1]; }
; #pragma unroll
;         for (int hh = 0; hh < 4; ++hh) { ss[hh] = wave_sum(dot4(v[2 * hh], v[2 * hh]) + dot4(v[2 * hh + 1], v[2 * hh + 1])); ss[hh] = 1.0f / sqrtf(ss[hh] * (1.0f / 512.0f) + EPS); }
; #pragma unroll
;         for (int j = 0; j < 8; ++j) { const f32x4 g = gh[j]; const v2u ow = ((const GAS v2u*)(Z2 + (size_t)r * D))[lane + 64 * j];
;             const f32x4 o = (f32x4){bflo(ow.x), bfhi(ow.x), bflo(ow.y), bfhi(ow.y)}; const f32x4 y = (v[j] * ss[j >> 1]) * g * o;
;             v2u w; w.x = pk2(y[0], y[1]); w.y = pk2(y[2], y[3]); ((GAS v2u*)(HA + (size_t)r * (2 * D)))[lane + 64 * j] = w; }
	v_add_f32_e32 v74, v83, v74
	v_fmamk_f32 v74, v74, 0x3b000000, v70
	v_mul_f32_e32 v75, 0x4f800000, v74
	v_cmp_gt_f32_e32 vcc, s13, v74
	s_nop 1
	v_cndmask_b32_e32 v76, v74, v75, vcc
	v_sqrt_f32_e32 v77, v76
	v_lshlrev_b32_e32 v74, 16, v116
	v_and_b32_e32 v75, 0xffff0000, v116
	v_lshlrev_b32_e32 v72, 16, v117
	v_and_b32_e32 v73, 0xffff0000, v117
	v_pk_mul_f32 v[58:59], v[58:59], v[72:73]
	v_pk_mul_f32 v[60:61], v[60:61], v[74:75]
	v_bfe_u32 v73, v58, 16, 1
	v_bfe_u32 v42, v60, 16, 1
	v_bfe_u32 v72, v61, 16, 1
	v_bfe_u32 v74, v59, 16, 1
	v_add3_u32 v42, v60, v42, s23
	v_add3_u32 v58, v58, v73, s23
	v_add3_u32 v60, v61, v72, s23
	v_add3_u32 v59, v59, v74, s23
	v_lshrrev_b32_e32 v42, 16, v42
	v_lshrrev_b32_e32 v61, 16, v58
	v_and_or_b32 v58, v60, s11, v42
	v_and_or_b32 v59, v59, s11, v61
	global_store_dwordx2 v[38:39], v[58:59], off offset:1536
	v_add_u32_e32 v78, -1, v77
	v_add_u32_e32 v79, 1, v77
	v_fma_f32 v42, -v78, v77, v76
	v_fma_f32 v60, -v79, v77, v76
	v_cmp_ge_f32_e64 s[0:1], 0, v42
	s_nop 1
	v_cndmask_b32_e64 v42, v77, v78, s[0:1]
	v_cmp_lt_f32_e64 s[0:1], 0, v60
	s_nop 1
	v_cndmask_b32_e64 v42, v42, v79, s[0:1]
	v_mul_f32_e32 v60, 0x37800000, v42
	v_cndmask_b32_e32 v42, v42, v60, vcc
	v_cmp_class_f32_e32 vcc, v76, v71
	s_nop 1
	v_cndmask_b32_e32 v42, v42, v76, vcc
	v_div_scale_f32 v60, s[0:1], v42, v42, 1.0
	v_rcp_f32_e32 v72, v60
	v_div_scale_f32 v61, vcc, 1.0, v42, 1.0
	v_fma_f32 v73, -v60, v72, 1.0
	v_fmac_f32_e32 v72, v73, v72
	v_mul_f32_e32 v73, v61, v72
	v_fma_f32 v74, -v60, v73, v61
	v_fmac_f32_e32 v73, v74, v72
	v_fma_f32 v60, -v60, v73, v61
	v_div_fmas_f32 v60, v60, v72, v73
	v_div_fixup_f32 v42, v60, v42, 1.0
	v_pk_mul_f32 v[54:55], v[54:55], v[42:43] op_sel_hi:[1,0]
	v_pk_mul_f32 v[56:57], v[56:57], v[42:43] op_sel_hi:[1,0]
	v_pk_mul_f32 v[54:55], v[20:21], v[54:55]
	v_pk_mul_f32 v[56:57], v[18:19], v[56:57]
	v_lshlrev_b32_e32 v60, 16, v118
	v_and_b32_e32 v61, 0xffff0000, v118
	v_lshlrev_b32_e32 v58, 16, v119
	v_and_b32_e32 v59, 0xffff0000, v119
	v_pk_mul_f32 v[54:55], v[54:55], v[58:59]
	v_pk_mul_f32 v[56:57], v[56:57], v[60:61]
	v_bfe_u32 v60, v54, 16, 1
	v_bfe_u32 v58, v56, 16, 1
	v_bfe_u32 v59, v57, 16, 1
	v_bfe_u32 v61, v55, 16, 1
	v_add3_u32 v56, v56, v58, s23
	v_add3_u32 v54, v54, v60, s23
	v_add3_u32 v57, v57, v59, s23
	v_add3_u32 v55, v55, v61, s23
	v_lshrrev_b32_e32 v56, 16, v56
	v_lshrrev_b32_e32 v58, 16, v54
	v_and_or_b32 v54, v57, s11, v56
	v_and_or_b32 v55, v55, s11, v58
	global_store_dwordx2 v[38:39], v[54:55], off offset:2048
	v_lshlrev_b32_e32 v56, 16, v43
	v_and_b32_e32 v57, 0xffff0000, v43
	v_div_fixup_f32 v58, v109, v108, 1.0
	v_pk_mul_f32 v[48:49], v[58:59], v[48:49] op_sel_hi:[0,1]
	v_pk_mul_f32 v[44:45], v[58:59], v[44:45] op_sel_hi:[0,1]
	v_pk_mul_f32 v[56:57], v[58:59], v[56:57] op_sel_hi:[0,1]
	v_pk_mul_f32 v[46:47], v[58:59], v[46:47] op_sel_hi:[0,1]
	v_mov_b32_e32 v60, v45
	v_mov_b32_e32 v61, v47
	v_mov_b32_e32 v74, v49
	v_mov_b32_e32 v75, v57
	v_mov_b32_e32 v58, v44
	v_mov_b32_e32 v59, v46
	v_mov_b32_e32 v72, v48
	v_mov_b32_e32 v73, v56
	v_pk_mul_f32 v[60:61], v[60:61], v[60:61]
	v_pk_mul_f32 v[74:75], v[74:75], v[74:75]
	v_pk_fma_f32 v[58:59], v[58:59], v[58:59], v[60:61]
	v_pk_fma_f32 v[60:61], v[72:73], v[72:73], v[74:75]
	s_nop 0
	v_pk_add_f32 v[58:59], v[58:59], v[60:61]
	s_nop 0
	v_add_f32_e32 v43, v58, v59
	ds_bpermute_b32 v58, v62, v43
	s_waitcnt lgkmcnt(0)
	v_add_f32_e32 v43, v43, v58
	ds_bpermute_b32 v58, v63, v43
	s_waitcnt lgkmcnt(0)
	v_add_f32_e32 v43, v43, v58
	ds_bpermute_b32 v58, v64, v43
	v_pk_mul_f32 v[50:51], v[50:51], v[42:43] op_sel_hi:[1,0]
	s_waitcnt lgkmcnt(0)
; #define GAS __attribute__((address_space(1)))
; __device__ __forceinline__ unsigned pk2(float lo, float hi) { return f2bf(lo) | (f2bf(hi) << 16); }
; __device__ __forceinline__ float bflo(unsigned w) { return __uint_as_float(w << 16); }
; __device__ __forceinline__ float bfhi(unsigned w) { return __uint_as_float(w & 0xffff0000u); }
; __device__ __forceinline__ float dot4(f32x4 a, f32x4 b) { return (a[0] * b[0] + a[1] * b[1]) + (a[2] * b[2] + a[3] * b[3]); }
; __device__ __forceinline__ void headnorm_all(Frame& F, const Args& a) {
;     ...
;     for (int r = gw; r < M; r += NGW) {
;         const GAS v2u* hp = (const GAS v2u*)(HRAW + (size_t)r * D) + lane; f32x4 v[8]; float ss[4];
;         f32x4 di;
; #pragma unroll
;         for (int hh = 0; hh < 4; ++hh) { const f32x4 x = *(const GAS f32x4*)(WSP(float, WS_DENINV) + ((size_t)r * 4 + hh) * 4); di[hh] = 1.0f / fmaxf(fabsf(x[0] + x[2]), x[1]); }
; #pragma unroll
;         for (int j = 0; j < 8; ++j) { const v2u hw = hp[64 * j]; v[j] = (f32x4){bflo(hw.x), bfhi(hw.x), bflo(hw.y), bfhi(hw.y)} * di[j >> 1]; }
; #pragma unroll
;         for (int hh = 0; hh < 4; ++hh) { ss[hh] = wave_sum(dot4(v[2 * hh], v[2 * hh]) + dot4(v[2 * hh + 1], v[2 * hh + 1])); ss[hh] = 1.0f / sqrtf(ss[hh] * (1.0f / 512.0f) + EPS); }
; #pragma unroll
;         for (int j = 0; j < 8; ++j) { const f32x4 g = gh[j]; const v2u ow = ((const GAS v2u*)(Z2 + (size_t)r * D))[lane + 64 * j];
;             const f32x4 o = (f32x4){bflo(ow.x), bfhi(ow.x), bflo(ow.y), bfhi(ow.y)}; const f32x4 y = (v[j] * ss[j >> 1]) * g * o;
;             v2u w; w.x = pk2(y[0], y[1]); w.y = pk2(y[2], y[3]); ((GAS v2u*)(HA + (size_t)r * (2 * D)))[lane + 64 * j] = w; }
;     }
	v_add_f32_e32 v58, v43, v58
	v_pk_mul_f32 v[42:43], v[52:53], v[42:43] op_sel_hi:[1,0]
	v_pk_mul_f32 v[50:51], v[24:25], v[50:51]
	v_pk_mul_f32 v[42:43], v[22:23], v[42:43]
	v_lshlrev_b32_e32 v52, 16, v120
	v_and_b32_e32 v53, 0xffff0000, v120
	v_lshlrev_b32_e32 v54, 16, v121
	v_and_b32_e32 v55, 0xffff0000, v121
	v_pk_mul_f32 v[50:51], v[50:51], v[54:55]
	v_pk_mul_f32 v[42:43], v[42:43], v[52:53]
	v_bfe_u32 v54, v50, 16, 1
	v_bfe_u32 v52, v42, 16, 1
	v_bfe_u32 v53, v43, 16, 1
	v_bfe_u32 v55, v51, 16, 1
	v_add3_u32 v42, v42, v52, s23
	v_add3_u32 v50, v50, v54, s23
	v_add3_u32 v43, v43, v53, s23
	v_add3_u32 v51, v51, v55, s23
	v_lshrrev_b32_e32 v42, 16, v42
	v_lshrrev_b32_e32 v50, 16, v50
	v_and_or_b32 v42, v43, s11, v42
	v_and_or_b32 v43, v51, s11, v50
	global_store_dwordx2 v[38:39], v[42:43], off offset:2560
	ds_bpermute_b32 v50, v65, v58
	s_waitcnt lgkmcnt(0)
	v_add_f32_e32 v50, v58, v50
	ds_bpermute_b32 v51, v66, v50
	s_waitcnt lgkmcnt(0)
	v_add_f32_e32 v50, v50, v51
	ds_bpermute_b32 v51, v67, v50
	s_waitcnt lgkmcnt(0)
	v_add_f32_e32 v50, v50, v51
	v_fmamk_f32 v50, v50, 0x3b000000, v70
	v_mul_f32_e32 v51, 0x4f800000, v50
	v_cmp_gt_f32_e32 vcc, s13, v50
	s_nop 1
	v_cndmask_b32_e32 v50, v50, v51, vcc
	v_sqrt_f32_e32 v51, v50
	s_nop 0
	v_add_u32_e32 v52, -1, v51
	v_add_u32_e32 v53, 1, v51
	v_fma_f32 v54, -v52, v51, v50
	v_fma_f32 v55, -v53, v51, v50
	v_cmp_ge_f32_e64 s[0:1], 0, v54
	s_nop 1
	v_cndmask_b32_e64 v51, v51, v52, s[0:1]
	v_cmp_lt_f32_e64 s[0:1], 0, v55
	s_nop 1
	v_cndmask_b32_e64 v51, v51, v53, s[0:1]
	v_mul_f32_e32 v52, 0x37800000, v51
	v_cndmask_b32_e32 v51, v51, v52, vcc
	v_cmp_class_f32_e32 vcc, v50, v71
	s_nop 1
	v_cndmask_b32_e32 v50, v51, v50, vcc
	v_div_scale_f32 v51, s[0:1], v50, v50, 1.0
	v_rcp_f32_e32 v53, v51
	v_div_scale_f32 v52, vcc, 1.0, v50, 1.0
	v_fma_f32 v54, -v51, v53, 1.0
	v_fmac_f32_e32 v53, v54, v53
	v_mul_f32_e32 v54, v52, v53
	v_fma_f32 v55, -v51, v54, v52
	v_fmac_f32_e32 v54, v55, v53
	v_fma_f32 v51, -v51, v54, v52
	v_div_fmas_f32 v51, v51, v53, v54
	v_div_fixup_f32 v50, v51, v50, 1.0
	v_pk_mul_f32 v[48:49], v[48:49], v[50:51] op_sel_hi:[1,0]
	v_pk_mul_f32 v[44:45], v[44:45], v[50:51] op_sel_hi:[1,0]
	v_pk_mul_f32 v[48:49], v[28:29], v[48:49]
	v_pk_mul_f32 v[44:45], v[26:27], v[44:45]
	v_lshlrev_b32_e32 v52, 16, v122
	v_and_b32_e32 v53, 0xffff0000, v122
	v_lshlrev_b32_e32 v42, 16, v123
	v_and_b32_e32 v43, 0xffff0000, v123
	v_pk_mul_f32 v[42:43], v[48:49], v[42:43]
	v_pk_mul_f32 v[44:45], v[44:45], v[52:53]
	v_bfe_u32 v51, v42, 16, 1
	v_bfe_u32 v48, v44, 16, 1
	v_bfe_u32 v49, v45, 16, 1
	v_bfe_u32 v52, v43, 16, 1
	v_add3_u32 v44, v44, v48, s23
	v_add3_u32 v42, v42, v51, s23
	v_add3_u32 v45, v45, v49, s23
	v_add3_u32 v43, v43, v52, s23
	v_lshrrev_b32_e32 v44, 16, v44
	v_lshrrev_b32_e32 v48, 16, v42
	v_and_or_b32 v42, v45, s11, v44
	v_and_or_b32 v43, v43, s11, v48
	global_store_dwordx2 v[38:39], v[42:43], off offset:3072
	v_pk_mul_f32 v[42:43], v[56:57], v[50:51] op_sel_hi:[1,0]
	v_pk_mul_f32 v[44:45], v[46:47], v[50:51] op_sel_hi:[1,0]
	v_pk_mul_f32 v[42:43], v[32:33], v[42:43]
	v_pk_mul_f32 v[44:45], v[30:31], v[44:45]
	v_lshlrev_b32_e32 v46, 16, v124
	v_and_b32_e32 v47, 0xffff0000, v124
	v_lshlrev_b32_e32 v40, 16, v125
	v_and_b32_e32 v41, 0xffff0000, v125
	v_pk_mul_f32 v[40:41], v[42:43], v[40:41]
	v_pk_mul_f32 v[42:43], v[44:45], v[46:47]
	v_bfe_u32 v46, v40, 16, 1
	v_bfe_u32 v44, v42, 16, 1
	v_bfe_u32 v45, v43, 16, 1
	v_bfe_u32 v47, v41, 16, 1
	v_add3_u32 v42, v42, v44, s23
	v_add3_u32 v40, v40, v46, s23
	v_add3_u32 v43, v43, v45, s23
	v_add3_u32 v41, v41, v47, s23
	v_lshrrev_b32_e32 v42, 16, v42
	v_lshrrev_b32_e32 v44, 16, v40
	v_and_or_b32 v40, v43, s11, v42
	v_and_or_b32 v41, v41, s11, v44
	global_store_dwordx2 v[38:39], v[40:41], off offset:3584
	s_cbranch_scc1 .LBB0_1136

; __device__ __forceinline__ void unpack8(u32x4 w, f32x4& lo, f32x4& hi) { lo = (f32x4){bfl(w.x), bfh(w.x), bfl(w.y), bfh(w.y)}; hi = (f32x4){bfl(w.z), bfh(w.z), bfl(w.w), bfh(w.w)}; }
;     __device__ __forceinline__ void mid(f32x4 (&acc)[2][2][4][2], const Unit& u, int wr, int wc, int fr, int fq) const {
;         int lo_ = fr * D + 8 * fq; asm volatile("" : "+v"(lo_));
;         const unsigned base = (unsigned)((u.pm * BM + wr * 64) * D + u.pn * BM + wc * 32) + (unsigned)lo_;
; #pragma unroll
;         for (int ai = 0; ai < 2; ++ai)
; #pragma unroll
;             for (int m = 0; m < 4; ++m) { const unsigned ro = base + (unsigned)((ai * HALF + m * 16) * D);
; #pragma unroll
;                 for (int bj = 0; bj < 2; ++bj) { const u32x4 aw = *(const u32x4*)(GA + ro + bj * HALF), bw = *(const u32x4*)(GB + ro + bj * HALF);
;                     f32x4 a0, a1, b0, b1; unpack8(aw, a0, a1); unpack8(bw, b0, b1);
; #pragma unroll
;                     for (int e = 0; e < 4; ++e) { acc[ai][bj][m][0][e] *= a0[e] * __builtin_amdgcn_rcpf(fmaxf(b0[e], 1e-20f)); acc[ai][bj][m][1][e] *= a1[e] * __builtin_amdgcn_rcpf(fmaxf(b1[e], 1e-20f)); } }
;                 asm volatile("" ::: "memory"); }
.LBB0_1200:
	s_cmpk_lg_i32 s30, 0x1000
	s_cbranch_scc1 .LBB0_1199
	v_add_u32_e32 v146, s58, v162
	v_lshlrev_b32_e32 v130, 1, v146
	v_add_u32_e32 v131, 0x10000, v130
	v_add_u32_e32 v132, 0x20000, v130
	v_add_u32_e32 v133, 0x30000, v130
	v_add_u32_e32 v134, 0x80000, v130
	v_add_u32_e32 v135, 0x90000, v130
	v_add_u32_e32 v136, 0xa0000, v130
	v_add_u32_e32 v137, 0xb0000, v130
	global_load_dwordx4 v[166:169], v130, s[6:7] offset:0
	global_load_dwordx4 v[170:173], v130, s[8:9] offset:0
	global_load_dwordx4 v[174:177], v130, s[6:7] offset:256
	global_load_dwordx4 v[178:181], v130, s[8:9] offset:256
	global_load_dwordx4 v[182:185], v131, s[6:7] offset:0
	global_load_dwordx4 v[186:189], v131, s[8:9] offset:0
	global_load_dwordx4 v[190:193], v131, s[6:7] offset:256
	global_load_dwordx4 v[194:197], v131, s[8:9] offset:256
	global_load_dwordx4 v[198:201], v132, s[6:7] offset:0
	global_load_dwordx4 v[202:205], v132, s[8:9] offset:0
	global_load_dwordx4 v[206:209], v132, s[6:7] offset:256
	global_load_dwordx4 v[210:213], v132, s[8:9] offset:256
	global_load_dwordx4 v[214:217], v133, s[6:7] offset:0
	global_load_dwordx4 v[218:221], v133, s[8:9] offset:0
	global_load_dwordx4 v[222:225], v133, s[6:7] offset:256
	global_load_dwordx4 v[226:229], v133, s[8:9] offset:256
	s_waitcnt vmcnt(14)
	v_lshlrev_b32_e32 v230, 16, v170
	v_and_b32_e32 v231, 0xffff0000, v170
	v_max_f32_e32 v230, v230, v230
	v_max_f32_e32 v231, v231, v231
	v_max_f32_e32 v230, 0x1e3ce508, v230
	v_max_f32_e32 v231, 0x1e3ce508, v231
	v_rcp_f32_e32 v232, v230
	v_rcp_f32_e32 v233, v231
	v_lshlrev_b32_e32 v234, 16, v166
	v_and_b32_e32 v235, 0xffff0000, v166
	v_pk_mul_f32 v[232:233], v[232:233], v[234:235]
	v_pk_mul_f32 v[126:127], v[126:127], v[232:233]
	v_lshlrev_b32_e32 v230, 16, v171
	v_and_b32_e32 v231, 0xffff0000, v171
	v_max_f32_e32 v230, v230, v230
	v_max_f32_e32 v231, v231, v231
	v_max_f32_e32 v230, 0x1e3ce508, v230
	v_max_f32_e32 v231, 0x1e3ce508, v231
	v_rcp_f32_e32 v232, v230
	v_rcp_f32_e32 v233, v231
	v_lshlrev_b32_e32 v234, 16, v167
	v_and_b32_e32 v235, 0xffff0000, v167
	v_pk_mul_f32 v[232:233], v[232:233], v[234:235]
	v_pk_mul_f32 v[128:129], v[128:129], v[232:233]
	v_lshlrev_b32_e32 v230, 16, v172
	v_and_b32_e32 v231, 0xffff0000, v172
	v_max_f32_e32 v230, v230, v230
	v_max_f32_e32 v231, v231, v231
	v_max_f32_e32 v230, 0x1e3ce508, v230
	v_max_f32_e32 v231, 0x1e3ce508, v231
	v_rcp_f32_e32 v232, v230
	v_rcp_f32_e32 v233, v231
	v_lshlrev_b32_e32 v234, 16, v168
	v_and_b32_e32 v235, 0xffff0000, v168
	v_pk_mul_f32 v[232:233], v[232:233], v[234:235]
	v_pk_mul_f32 v[122:123], v[122:123], v[232:233]
	v_lshlrev_b32_e32 v230, 16, v173
	v_and_b32_e32 v231, 0xffff0000, v173
	v_max_f32_e32 v230, v230, v230
	v_max_f32_e32 v231, v231, v231
	v_max_f32_e32 v230, 0x1e3ce508, v230
	v_max_f32_e32 v231, 0x1e3ce508, v231
	v_rcp_f32_e32 v232, v230
	v_rcp_f32_e32 v233, v231
	v_lshlrev_b32_e32 v234, 16, v169
	v_and_b32_e32 v235, 0xffff0000, v169
	v_pk_mul_f32 v[232:233], v[232:233], v[234:235]
	v_pk_mul_f32 v[124:125], v[124:125], v[232:233]
	global_load_dwordx4 v[166:169], v134, s[6:7] offset:0
	global_load_dwordx4 v[170:173], v134, s[8:9] offset:0
	s_waitcnt vmcnt(14)
	v_lshlrev_b32_e32 v230, 16, v178
	v_and_b32_e32 v231, 0xffff0000, v178
	v_max_f32_e32 v230, v230, v230
	v_max_f32_e32 v231, v231, v231
	v_max_f32_e32 v230, 0x1e3ce508, v230
	v_max_f32_e32 v231, 0x1e3ce508, v231
	v_rcp_f32_e32 v232, v230
	v_rcp_f32_e32 v233, v231
	v_lshlrev_b32_e32 v234, 16, v174
	v_and_b32_e32 v235, 0xffff0000, v174
	v_pk_mul_f32 v[232:233], v[232:233], v[234:235]
	v_pk_mul_f32 v[118:119], v[118:119], v[232:233]
	v_lshlrev_b32_e32 v230, 16, v179
	v_and_b32_e32 v231, 0xffff0000, v179
	v_max_f32_e32 v230, v230, v230
	v_max_f32_e32 v231, v231, v231
	v_max_f32_e32 v230, 0x1e3ce508, v230
	v_max_f32_e32 v231, 0x1e3ce508, v231
	v_rcp_f32_e32 v232, v230
	v_rcp_f32_e32 v233, v231
	v_lshlrev_b32_e32 v234, 16, v175
	v_and_b32_e32 v235, 0xffff0000, v175
	v_pk_mul_f32 v[232:233], v[232:233], v[234:235]
	v_pk_mul_f32 v[120:121], v[120:121], v[232:233]
	v_lshlrev_b32_e32 v230, 16, v180
	v_and_b32_e32 v231, 0xffff0000, v180
	v_max_f32_e32 v230, v230, v230
	v_max_f32_e32 v231, v231, v231
	v_max_f32_e32 v230, 0x1e3ce508, v230
	v_max_f32_e32 v231, 0x1e3ce508, v231
	v_rcp_f32_e32 v232, v230
	v_rcp_f32_e32 v233, v231
	v_lshlrev_b32_e32 v234, 16, v176
	v_and_b32_e32 v235, 0xffff0000, v176
	v_pk_mul_f32 v[232:233], v[232:233], v[234:235]
	v_pk_mul_f32 v[114:115], v[114:115], v[232:233]
	v_lshlrev_b32_e32 v230, 16, v181
	v_and_b32_e32 v231, 0xffff0000, v181
	v_max_f32_e32 v230, v230, v230
	v_max_f32_e32 v231, v231, v231
	v_max_f32_e32 v230, 0x1e3ce508, v230
	v_max_f32_e32 v231, 0x1e3ce508, v231
	v_rcp_f32_e32 v232, v230
	v_rcp_f32_e32 v233, v231
	v_lshlrev_b32_e32 v234, 16, v177
	v_and_b32_e32 v235, 0xffff0000, v177
	v_pk_mul_f32 v[232:233], v[232:233], v[234:235]
	v_pk_mul_f32 v[116:117], v[116:117], v[232:233]
	global_load_dwordx4 v[174:177], v134, s[6:7] offset:256
	global_load_dwordx4 v[178:181], v134, s[8:9] offset:256
	s_waitcnt vmcnt(14)
; __device__ __forceinline__ void unpack8(u32x4 w, f32x4& lo, f32x4& hi) { lo = (f32x4){bfl(w.x), bfh(w.x), bfl(w.y), bfh(w.y)}; hi = (f32x4){bfl(w.z), bfh(w.z), bfl(w.w), bfh(w.w)}; }
;     __device__ __forceinline__ void mid(f32x4 (&acc)[2][2][4][2], const Unit& u, int wr, int wc, int fr, int fq) const {
;     ...
;             for (int m = 0; m < 4; ++m) { const unsigned ro = base + (unsigned)((ai * HALF + m * 16) * D);
; #pragma unroll
;                 for (int bj = 0; bj < 2; ++bj) { const u32x4 aw = *(const u32x4*)(GA + ro + bj * HALF), bw = *(const u32x4*)(GB + ro + bj * HALF);
;                     f32x4 a0, a1, b0, b1; unpack8(aw, a0, a1); unpack8(bw, b0, b1);
; #pragma unroll
;                     for (int e = 0; e < 4; ++e) { acc[ai][bj][m][0][e] *= a0[e] * __builtin_amdgcn_rcpf(fmaxf(b0[e], 1e-20f)); acc[ai][bj][m][1][e] *= a1[e] * __builtin_amdgcn_rcpf(fmaxf(b1[e], 1e-20f)); } }
	v_lshlrev_b32_e32 v230, 16, v186
	v_and_b32_e32 v231, 0xffff0000, v186
	v_max_f32_e32 v230, v230, v230
	v_max_f32_e32 v231, v231, v231
	v_max_f32_e32 v230, 0x1e3ce508, v230
	v_max_f32_e32 v231, 0x1e3ce508, v231
	v_rcp_f32_e32 v232, v230
	v_rcp_f32_e32 v233, v231
	v_lshlrev_b32_e32 v234, 16, v182
	v_and_b32_e32 v235, 0xffff0000, v182
	v_pk_mul_f32 v[232:233], v[232:233], v[234:235]
	v_pk_mul_f32 v[110:111], v[110:111], v[232:233]
	v_lshlrev_b32_e32 v230, 16, v187
	v_and_b32_e32 v231, 0xffff0000, v187
	v_max_f32_e32 v230, v230, v230
	v_max_f32_e32 v231, v231, v231
	v_max_f32_e32 v230, 0x1e3ce508, v230
	v_max_f32_e32 v231, 0x1e3ce508, v231
	v_rcp_f32_e32 v232, v230
	v_rcp_f32_e32 v233, v231
	v_lshlrev_b32_e32 v234, 16, v183
	v_and_b32_e32 v235, 0xffff0000, v183
	v_pk_mul_f32 v[232:233], v[232:233], v[234:235]
	v_pk_mul_f32 v[112:113], v[112:113], v[232:233]
	v_lshlrev_b32_e32 v230, 16, v188
	v_and_b32_e32 v231, 0xffff0000, v188
	v_max_f32_e32 v230, v230, v230
	v_max_f32_e32 v231, v231, v231
	v_max_f32_e32 v230, 0x1e3ce508, v230
	v_max_f32_e32 v231, 0x1e3ce508, v231
	v_rcp_f32_e32 v232, v230
	v_rcp_f32_e32 v233, v231
	v_lshlrev_b32_e32 v234, 16, v184
	v_and_b32_e32 v235, 0xffff0000, v184
	v_pk_mul_f32 v[232:233], v[232:233], v[234:235]
	v_pk_mul_f32 v[106:107], v[106:107], v[232:233]
	v_lshlrev_b32_e32 v230, 16, v189
	v_and_b32_e32 v231, 0xffff0000, v189
	v_max_f32_e32 v230, v230, v230
	v_max_f32_e32 v231, v231, v231
	v_max_f32_e32 v230, 0x1e3ce508, v230
	v_max_f32_e32 v231, 0x1e3ce508, v231
	v_rcp_f32_e32 v232, v230
	v_rcp_f32_e32 v233, v231
	v_lshlrev_b32_e32 v234, 16, v185
	v_and_b32_e32 v235, 0xffff0000, v185
	v_pk_mul_f32 v[232:233], v[232:233], v[234:235]
	v_pk_mul_f32 v[108:109], v[108:109], v[232:233]
	global_load_dwordx4 v[182:185], v135, s[6:7] offset:0
	global_load_dwordx4 v[186:189], v135, s[8:9] offset:0
	s_waitcnt vmcnt(14)
	v_lshlrev_b32_e32 v230, 16, v194
	v_and_b32_e32 v231, 0xffff0000, v194
	v_max_f32_e32 v230, v230, v230
	v_max_f32_e32 v231, v231, v231
	v_max_f32_e32 v230, 0x1e3ce508, v230
	v_max_f32_e32 v231, 0x1e3ce508, v231
	v_rcp_f32_e32 v232, v230
	v_rcp_f32_e32 v233, v231
	v_lshlrev_b32_e32 v234, 16, v190
	v_and_b32_e32 v235, 0xffff0000, v190
	v_pk_mul_f32 v[232:233], v[232:233], v[234:235]
	v_pk_mul_f32 v[102:103], v[102:103], v[232:233]
	v_lshlrev_b32_e32 v230, 16, v195
	v_and_b32_e32 v231, 0xffff0000, v195
	v_max_f32_e32 v230, v230, v230
	v_max_f32_e32 v231, v231, v231
	v_max_f32_e32 v230, 0x1e3ce508, v230
	v_max_f32_e32 v231, 0x1e3ce508, v231
	v_rcp_f32_e32 v232, v230
	v_rcp_f32_e32 v233, v231
	v_lshlrev_b32_e32 v234, 16, v191
	v_and_b32_e32 v235, 0xffff0000, v191
	v_pk_mul_f32 v[232:233], v[232:233], v[234:235]
	v_pk_mul_f32 v[104:105], v[104:105], v[232:233]
	v_lshlrev_b32_e32 v230, 16, v196
	v_and_b32_e32 v231, 0xffff0000, v196
	v_max_f32_e32 v230, v230, v230
	v_max_f32_e32 v231, v231, v231
	v_max_f32_e32 v230, 0x1e3ce508, v230
	v_max_f32_e32 v231, 0x1e3ce508, v231
	v_rcp_f32_e32 v232, v230
	v_rcp_f32_e32 v233, v231
	v_lshlrev_b32_e32 v234, 16, v192
	v_and_b32_e32 v235, 0xffff0000, v192
	v_pk_mul_f32 v[232:233], v[232:233], v[234:235]
	v_pk_mul_f32 v[98:99], v[98:99], v[232:233]
	v_lshlrev_b32_e32 v230, 16, v197
	v_and_b32_e32 v231, 0xffff0000, v197
	v_max_f32_e32 v230, v230, v230
	v_max_f32_e32 v231, v231, v231
	v_max_f32_e32 v230, 0x1e3ce508, v230
	v_max_f32_e32 v231, 0x1e3ce508, v231
	v_rcp_f32_e32 v232, v230
	v_rcp_f32_e32 v233, v231
	v_lshlrev_b32_e32 v234, 16, v193
	v_and_b32_e32 v235, 0xffff0000, v193
	v_pk_mul_f32 v[232:233], v[232:233], v[234:235]
	v_pk_mul_f32 v[100:101], v[100:101], v[232:233]
	global_load_dwordx4 v[190:193], v135, s[6:7] offset:256
	global_load_dwordx4 v[194:197], v135, s[8:9] offset:256
	s_waitcnt vmcnt(14)
	v_lshlrev_b32_e32 v230, 16, v202
	v_and_b32_e32 v231, 0xffff0000, v202
	v_max_f32_e32 v230, v230, v230
	v_max_f32_e32 v231, v231, v231
	v_max_f32_e32 v230, 0x1e3ce508, v230
	v_max_f32_e32 v231, 0x1e3ce508, v231
	v_rcp_f32_e32 v232, v230
	v_rcp_f32_e32 v233, v231
	v_lshlrev_b32_e32 v234, 16, v198
	v_and_b32_e32 v235, 0xffff0000, v198
	v_pk_mul_f32 v[232:233], v[232:233], v[234:235]
	v_pk_mul_f32 v[94:95], v[94:95], v[232:233]
	v_lshlrev_b32_e32 v230, 16, v203
	v_and_b32_e32 v231, 0xffff0000, v203
	v_max_f32_e32 v230, v230, v230
	v_max_f32_e32 v231, v231, v231
	v_max_f32_e32 v230, 0x1e3ce508, v230
	v_max_f32_e32 v231, 0x1e3ce508, v231
	v_rcp_f32_e32 v232, v230
	v_rcp_f32_e32 v233, v231
	v_lshlrev_b32_e32 v234, 16, v199
	v_and_b32_e32 v235, 0xffff0000, v199
	v_pk_mul_f32 v[232:233], v[232:233], v[234:235]
	v_pk_mul_f32 v[96:97], v[96:97], v[232:233]
	v_lshlrev_b32_e32 v230, 16, v204
	v_and_b32_e32 v231, 0xffff0000, v204
	v_max_f32_e32 v230, v230, v230
	v_max_f32_e32 v231, v231, v231
	v_max_f32_e32 v230, 0x1e3ce508, v230
	v_max_f32_e32 v231, 0x1e3ce508, v231
	v_rcp_f32_e32 v232, v230
	v_rcp_f32_e32 v233, v231
	v_lshlrev_b32_e32 v234, 16, v200
	v_and_b32_e32 v235, 0xffff0000, v200
	v_pk_mul_f32 v[232:233], v[232:233], v[234:235]
	v_pk_mul_f32 v[90:91], v[90:91], v[232:233]
	v_lshlrev_b32_e32 v230, 16, v205
	v_and_b32_e32 v231, 0xffff0000, v205
	v_max_f32_e32 v230, v230, v230
	v_max_f32_e32 v231, v231, v231
	v_max_f32_e32 v230, 0x1e3ce508, v230
	v_max_f32_e32 v231, 0x1e3ce508, v231
	v_rcp_f32_e32 v232, v230
	v_rcp_f32_e32 v233, v231
	v_lshlrev_b32_e32 v234, 16, v201
	v_and_b32_e32 v235, 0xffff0000, v201
	v_pk_mul_f32 v[232:233], v[232:233], v[234:235]
	v_pk_mul_f32 v[92:93], v[92:93], v[232:233]
	global_load_dwordx4 v[198:201], v136, s[6:7] offset:0
	global_load_dwordx4 v[202:205], v136, s[8:9] offset:0
	s_waitcnt vmcnt(14)
; __device__ __forceinline__ void unpack8(u32x4 w, f32x4& lo, f32x4& hi) { lo = (f32x4){bfl(w.x), bfh(w.x), bfl(w.y), bfh(w.y)}; hi = (f32x4){bfl(w.z), bfh(w.z), bfl(w.w), bfh(w.w)}; }
;     __device__ __forceinline__ void mid(f32x4 (&acc)[2][2][4][2], const Unit& u, int wr, int wc, int fr, int fq) const {
;     ...
;             for (int m = 0; m < 4; ++m) { const unsigned ro = base + (unsigned)((ai * HALF + m * 16) * D);
; #pragma unroll
;                 for (int bj = 0; bj < 2; ++bj) { const u32x4 aw = *(const u32x4*)(GA + ro + bj * HALF), bw = *(const u32x4*)(GB + ro + bj * HALF);
;                     f32x4 a0, a1, b0, b1; unpack8(aw, a0, a1); unpack8(bw, b0, b1);
; #pragma unroll
;                     for (int e = 0; e < 4; ++e) { acc[ai][bj][m][0][e] *= a0[e] * __builtin_amdgcn_rcpf(fmaxf(b0[e], 1e-20f)); acc[ai][bj][m][1][e] *= a1[e] * __builtin_amdgcn_rcpf(fmaxf(b1[e], 1e-20f)); } }
	v_lshlrev_b32_e32 v230, 16, v210
	v_and_b32_e32 v231, 0xffff0000, v210
	v_max_f32_e32 v230, v230, v230
	v_max_f32_e32 v231, v231, v231
	v_max_f32_e32 v230, 0x1e3ce508, v230
	v_max_f32_e32 v231, 0x1e3ce508, v231
	v_rcp_f32_e32 v232, v230
	v_rcp_f32_e32 v233, v231
	v_lshlrev_b32_e32 v234, 16, v206
	v_and_b32_e32 v235, 0xffff0000, v206
	v_pk_mul_f32 v[232:233], v[232:233], v[234:235]
	v_pk_mul_f32 v[86:87], v[86:87], v[232:233]
	v_lshlrev_b32_e32 v230, 16, v211
	v_and_b32_e32 v231, 0xffff0000, v211
	v_max_f32_e32 v230, v230, v230
	v_max_f32_e32 v231, v231, v231
	v_max_f32_e32 v230, 0x1e3ce508, v230
	v_max_f32_e32 v231, 0x1e3ce508, v231
	v_rcp_f32_e32 v232, v230
	v_rcp_f32_e32 v233, v231
	v_lshlrev_b32_e32 v234, 16, v207
	v_and_b32_e32 v235, 0xffff0000, v207
	v_pk_mul_f32 v[232:233], v[232:233], v[234:235]
	v_pk_mul_f32 v[88:89], v[88:89], v[232:233]
	v_lshlrev_b32_e32 v230, 16, v212
	v_and_b32_e32 v231, 0xffff0000, v212
	v_max_f32_e32 v230, v230, v230
	v_max_f32_e32 v231, v231, v231
	v_max_f32_e32 v230, 0x1e3ce508, v230
	v_max_f32_e32 v231, 0x1e3ce508, v231
	v_rcp_f32_e32 v232, v230
	v_rcp_f32_e32 v233, v231
	v_lshlrev_b32_e32 v234, 16, v208
	v_and_b32_e32 v235, 0xffff0000, v208
	v_pk_mul_f32 v[232:233], v[232:233], v[234:235]
	v_pk_mul_f32 v[82:83], v[82:83], v[232:233]
	v_lshlrev_b32_e32 v230, 16, v213
	v_and_b32_e32 v231, 0xffff0000, v213
	v_max_f32_e32 v230, v230, v230
	v_max_f32_e32 v231, v231, v231
	v_max_f32_e32 v230, 0x1e3ce508, v230
	v_max_f32_e32 v231, 0x1e3ce508, v231
	v_rcp_f32_e32 v232, v230
	v_rcp_f32_e32 v233, v231
	v_lshlrev_b32_e32 v234, 16, v209
	v_and_b32_e32 v235, 0xffff0000, v209
	v_pk_mul_f32 v[232:233], v[232:233], v[234:235]
	v_pk_mul_f32 v[84:85], v[84:85], v[232:233]
	global_load_dwordx4 v[206:209], v136, s[6:7] offset:256
	global_load_dwordx4 v[210:213], v136, s[8:9] offset:256
	s_waitcnt vmcnt(14)
	v_lshlrev_b32_e32 v230, 16, v218
	v_and_b32_e32 v231, 0xffff0000, v218
	v_max_f32_e32 v230, v230, v230
	v_max_f32_e32 v231, v231, v231
	v_max_f32_e32 v230, 0x1e3ce508, v230
	v_max_f32_e32 v231, 0x1e3ce508, v231
	v_rcp_f32_e32 v232, v230
	v_rcp_f32_e32 v233, v231
	v_lshlrev_b32_e32 v234, 16, v214
	v_and_b32_e32 v235, 0xffff0000, v214
	v_pk_mul_f32 v[232:233], v[232:233], v[234:235]
	v_pk_mul_f32 v[78:79], v[78:79], v[232:233]
	v_lshlrev_b32_e32 v230, 16, v219
	v_and_b32_e32 v231, 0xffff0000, v219
	v_max_f32_e32 v230, v230, v230
	v_max_f32_e32 v231, v231, v231
	v_max_f32_e32 v230, 0x1e3ce508, v230
	v_max_f32_e32 v231, 0x1e3ce508, v231
	v_rcp_f32_e32 v232, v230
	v_rcp_f32_e32 v233, v231
	v_lshlrev_b32_e32 v234, 16, v215
	v_and_b32_e32 v235, 0xffff0000, v215
	v_pk_mul_f32 v[232:233], v[232:233], v[234:235]
	v_pk_mul_f32 v[80:81], v[80:81], v[232:233]
	v_lshlrev_b32_e32 v230, 16, v220
	v_and_b32_e32 v231, 0xffff0000, v220
	v_max_f32_e32 v230, v230, v230
	v_max_f32_e32 v231, v231, v231
	v_max_f32_e32 v230, 0x1e3ce508, v230
	v_max_f32_e32 v231, 0x1e3ce508, v231
	v_rcp_f32_e32 v232, v230
	v_rcp_f32_e32 v233, v231
	v_lshlrev_b32_e32 v234, 16, v216
	v_and_b32_e32 v235, 0xffff0000, v216
	v_pk_mul_f32 v[232:233], v[232:233], v[234:235]
	v_pk_mul_f32 v[74:75], v[74:75], v[232:233]
	v_lshlrev_b32_e32 v230, 16, v221
	v_and_b32_e32 v231, 0xffff0000, v221
	v_max_f32_e32 v230, v230, v230
	v_max_f32_e32 v231, v231, v231
	v_max_f32_e32 v230, 0x1e3ce508, v230
	v_max_f32_e32 v231, 0x1e3ce508, v231
	v_rcp_f32_e32 v232, v230
	v_rcp_f32_e32 v233, v231
	v_lshlrev_b32_e32 v234, 16, v217
	v_and_b32_e32 v235, 0xffff0000, v217
	v_pk_mul_f32 v[232:233], v[232:233], v[234:235]
	v_pk_mul_f32 v[76:77], v[76:77], v[232:233]
	global_load_dwordx4 v[214:217], v137, s[6:7] offset:0
	global_load_dwordx4 v[218:221], v137, s[8:9] offset:0
	s_waitcnt vmcnt(14)
	v_lshlrev_b32_e32 v230, 16, v226
	v_and_b32_e32 v231, 0xffff0000, v226
	v_max_f32_e32 v230, v230, v230
	v_max_f32_e32 v231, v231, v231
	v_max_f32_e32 v230, 0x1e3ce508, v230
	v_max_f32_e32 v231, 0x1e3ce508, v231
	v_rcp_f32_e32 v232, v230
	v_rcp_f32_e32 v233, v231
	v_lshlrev_b32_e32 v234, 16, v222
	v_and_b32_e32 v235, 0xffff0000, v222
	v_pk_mul_f32 v[232:233], v[232:233], v[234:235]
	v_pk_mul_f32 v[70:71], v[70:71], v[232:233]
	v_lshlrev_b32_e32 v230, 16, v227
	v_and_b32_e32 v231, 0xffff0000, v227
	v_max_f32_e32 v230, v230, v230
	v_max_f32_e32 v231, v231, v231
	v_max_f32_e32 v230, 0x1e3ce508, v230
	v_max_f32_e32 v231, 0x1e3ce508, v231
	v_rcp_f32_e32 v232, v230
	v_rcp_f32_e32 v233, v231
	v_lshlrev_b32_e32 v234, 16, v223
	v_and_b32_e32 v235, 0xffff0000, v223
	v_pk_mul_f32 v[232:233], v[232:233], v[234:235]
	v_pk_mul_f32 v[72:73], v[72:73], v[232:233]
	v_lshlrev_b32_e32 v230, 16, v228
	v_and_b32_e32 v231, 0xffff0000, v228
	v_max_f32_e32 v230, v230, v230
	v_max_f32_e32 v231, v231, v231
	v_max_f32_e32 v230, 0x1e3ce508, v230
	v_max_f32_e32 v231, 0x1e3ce508, v231
	v_rcp_f32_e32 v232, v230
	v_rcp_f32_e32 v233, v231
	v_lshlrev_b32_e32 v234, 16, v224
	v_and_b32_e32 v235, 0xffff0000, v224
	v_pk_mul_f32 v[232:233], v[232:233], v[234:235]
	v_pk_mul_f32 v[66:67], v[66:67], v[232:233]
	v_lshlrev_b32_e32 v230, 16, v229
	v_and_b32_e32 v231, 0xffff0000, v229
	v_max_f32_e32 v230, v230, v230
	v_max_f32_e32 v231, v231, v231
	v_max_f32_e32 v230, 0x1e3ce508, v230
	v_max_f32_e32 v231, 0x1e3ce508, v231
	v_rcp_f32_e32 v232, v230
	v_rcp_f32_e32 v233, v231
	v_lshlrev_b32_e32 v234, 16, v225
	v_and_b32_e32 v235, 0xffff0000, v225
	v_pk_mul_f32 v[232:233], v[232:233], v[234:235]
	v_pk_mul_f32 v[68:69], v[68:69], v[232:233]
	global_load_dwordx4 v[222:225], v137, s[6:7] offset:256
	global_load_dwordx4 v[226:229], v137, s[8:9] offset:256
	s_waitcnt vmcnt(14)
; __device__ __forceinline__ void unpack8(u32x4 w, f32x4& lo, f32x4& hi) { lo = (f32x4){bfl(w.x), bfh(w.x), bfl(w.y), bfh(w.y)}; hi = (f32x4){bfl(w.z), bfh(w.z), bfl(w.w), bfh(w.w)}; }
;     __device__ __forceinline__ void mid(f32x4 (&acc)[2][2][4][2], const Unit& u, int wr, int wc, int fr, int fq) const {
;     ...
;             for (int m = 0; m < 4; ++m) { const unsigned ro = base + (unsigned)((ai * HALF + m * 16) * D);
; #pragma unroll
;                 for (int bj = 0; bj < 2; ++bj) { const u32x4 aw = *(const u32x4*)(GA + ro + bj * HALF), bw = *(const u32x4*)(GB + ro + bj * HALF);
;                     f32x4 a0, a1, b0, b1; unpack8(aw, a0, a1); unpack8(bw, b0, b1);
; #pragma unroll
;                     for (int e = 0; e < 4; ++e) { acc[ai][bj][m][0][e] *= a0[e] * __builtin_amdgcn_rcpf(fmaxf(b0[e], 1e-20f)); acc[ai][bj][m][1][e] *= a1[e] * __builtin_amdgcn_rcpf(fmaxf(b1[e], 1e-20f)); } }
	v_lshlrev_b32_e32 v230, 16, v170
	v_and_b32_e32 v231, 0xffff0000, v170
	v_max_f32_e32 v230, v230, v230
	v_max_f32_e32 v231, v231, v231
	v_max_f32_e32 v230, 0x1e3ce508, v230
	v_max_f32_e32 v231, 0x1e3ce508, v231
	v_rcp_f32_e32 v232, v230
	v_rcp_f32_e32 v233, v231
	v_lshlrev_b32_e32 v234, 16, v166
	v_and_b32_e32 v235, 0xffff0000, v166
	v_pk_mul_f32 v[232:233], v[232:233], v[234:235]
	v_pk_mul_f32 v[62:63], v[62:63], v[232:233]
	v_lshlrev_b32_e32 v230, 16, v171
	v_and_b32_e32 v231, 0xffff0000, v171
	v_max_f32_e32 v230, v230, v230
	v_max_f32_e32 v231, v231, v231
	v_max_f32_e32 v230, 0x1e3ce508, v230
	v_max_f32_e32 v231, 0x1e3ce508, v231
	v_rcp_f32_e32 v232, v230
	v_rcp_f32_e32 v233, v231
	v_lshlrev_b32_e32 v234, 16, v167
	v_and_b32_e32 v235, 0xffff0000, v167
	v_pk_mul_f32 v[232:233], v[232:233], v[234:235]
	v_pk_mul_f32 v[64:65], v[64:65], v[232:233]
	v_lshlrev_b32_e32 v230, 16, v172
	v_and_b32_e32 v231, 0xffff0000, v172
	v_max_f32_e32 v230, v230, v230
	v_max_f32_e32 v231, v231, v231
	v_max_f32_e32 v230, 0x1e3ce508, v230
	v_max_f32_e32 v231, 0x1e3ce508, v231
	v_rcp_f32_e32 v232, v230
	v_rcp_f32_e32 v233, v231
	v_lshlrev_b32_e32 v234, 16, v168
	v_and_b32_e32 v235, 0xffff0000, v168
	v_pk_mul_f32 v[232:233], v[232:233], v[234:235]
	v_pk_mul_f32 v[58:59], v[58:59], v[232:233]
	v_lshlrev_b32_e32 v230, 16, v173
	v_and_b32_e32 v231, 0xffff0000, v173
	v_max_f32_e32 v230, v230, v230
	v_max_f32_e32 v231, v231, v231
	v_max_f32_e32 v230, 0x1e3ce508, v230
	v_max_f32_e32 v231, 0x1e3ce508, v231
	v_rcp_f32_e32 v232, v230
	v_rcp_f32_e32 v233, v231
	v_lshlrev_b32_e32 v234, 16, v169
	v_and_b32_e32 v235, 0xffff0000, v169
	v_pk_mul_f32 v[232:233], v[232:233], v[234:235]
	v_pk_mul_f32 v[60:61], v[60:61], v[232:233]
	s_waitcnt vmcnt(12)
	v_lshlrev_b32_e32 v230, 16, v178
	v_and_b32_e32 v231, 0xffff0000, v178
	v_max_f32_e32 v230, v230, v230
	v_max_f32_e32 v231, v231, v231
	v_max_f32_e32 v230, 0x1e3ce508, v230
	v_max_f32_e32 v231, 0x1e3ce508, v231
	v_rcp_f32_e32 v232, v230
	v_rcp_f32_e32 v233, v231
	v_lshlrev_b32_e32 v234, 16, v174
	v_and_b32_e32 v235, 0xffff0000, v174
	v_pk_mul_f32 v[232:233], v[232:233], v[234:235]
	v_pk_mul_f32 v[54:55], v[54:55], v[232:233]
	v_lshlrev_b32_e32 v230, 16, v179
	v_and_b32_e32 v231, 0xffff0000, v179
	v_max_f32_e32 v230, v230, v230
	v_max_f32_e32 v231, v231, v231
	v_max_f32_e32 v230, 0x1e3ce508, v230
	v_max_f32_e32 v231, 0x1e3ce508, v231
	v_rcp_f32_e32 v232, v230
	v_rcp_f32_e32 v233, v231
	v_lshlrev_b32_e32 v234, 16, v175
	v_and_b32_e32 v235, 0xffff0000, v175
	v_pk_mul_f32 v[232:233], v[232:233], v[234:235]
	v_pk_mul_f32 v[56:57], v[56:57], v[232:233]
	v_lshlrev_b32_e32 v230, 16, v180
	v_and_b32_e32 v231, 0xffff0000, v180
	v_max_f32_e32 v230, v230, v230
	v_max_f32_e32 v231, v231, v231
	v_max_f32_e32 v230, 0x1e3ce508, v230
	v_max_f32_e32 v231, 0x1e3ce508, v231
	v_rcp_f32_e32 v232, v230
	v_rcp_f32_e32 v233, v231
	v_lshlrev_b32_e32 v234, 16, v176
	v_and_b32_e32 v235, 0xffff0000, v176
	v_pk_mul_f32 v[232:233], v[232:233], v[234:235]
	v_pk_mul_f32 v[50:51], v[50:51], v[232:233]
	v_lshlrev_b32_e32 v230, 16, v181
	v_and_b32_e32 v231, 0xffff0000, v181
	v_max_f32_e32 v230, v230, v230
	v_max_f32_e32 v231, v231, v231
	v_max_f32_e32 v230, 0x1e3ce508, v230
	v_max_f32_e32 v231, 0x1e3ce508, v231
	v_rcp_f32_e32 v232, v230
	v_rcp_f32_e32 v233, v231
	v_lshlrev_b32_e32 v234, 16, v177
	v_and_b32_e32 v235, 0xffff0000, v177
	v_pk_mul_f32 v[232:233], v[232:233], v[234:235]
	v_pk_mul_f32 v[52:53], v[52:53], v[232:233]
	s_waitcnt vmcnt(10)
	v_lshlrev_b32_e32 v230, 16, v186
	v_and_b32_e32 v231, 0xffff0000, v186
	v_max_f32_e32 v230, v230, v230
	v_max_f32_e32 v231, v231, v231
	v_max_f32_e32 v230, 0x1e3ce508, v230
	v_max_f32_e32 v231, 0x1e3ce508, v231
	v_rcp_f32_e32 v232, v230
	v_rcp_f32_e32 v233, v231
	v_lshlrev_b32_e32 v234, 16, v182
	v_and_b32_e32 v235, 0xffff0000, v182
	v_pk_mul_f32 v[232:233], v[232:233], v[234:235]
	v_pk_mul_f32 v[46:47], v[46:47], v[232:233]
	v_lshlrev_b32_e32 v230, 16, v187
	v_and_b32_e32 v231, 0xffff0000, v187
	v_max_f32_e32 v230, v230, v230
	v_max_f32_e32 v231, v231, v231
	v_max_f32_e32 v230, 0x1e3ce508, v230
	v_max_f32_e32 v231, 0x1e3ce508, v231
	v_rcp_f32_e32 v232, v230
	v_rcp_f32_e32 v233, v231
	v_lshlrev_b32_e32 v234, 16, v183
	v_and_b32_e32 v235, 0xffff0000, v183
	v_pk_mul_f32 v[232:233], v[232:233], v[234:235]
	v_pk_mul_f32 v[48:49], v[48:49], v[232:233]
	v_lshlrev_b32_e32 v230, 16, v188
	v_and_b32_e32 v231, 0xffff0000, v188
	v_max_f32_e32 v230, v230, v230
	v_max_f32_e32 v231, v231, v231
	v_max_f32_e32 v230, 0x1e3ce508, v230
	v_max_f32_e32 v231, 0x1e3ce508, v231
	v_rcp_f32_e32 v232, v230
	v_rcp_f32_e32 v233, v231
	v_lshlrev_b32_e32 v234, 16, v184
	v_and_b32_e32 v235, 0xffff0000, v184
	v_pk_mul_f32 v[232:233], v[232:233], v[234:235]
	v_pk_mul_f32 v[42:43], v[42:43], v[232:233]
	v_lshlrev_b32_e32 v230, 16, v189
	v_and_b32_e32 v231, 0xffff0000, v189
	v_max_f32_e32 v230, v230, v230
	v_max_f32_e32 v231, v231, v231
	v_max_f32_e32 v230, 0x1e3ce508, v230
	v_max_f32_e32 v231, 0x1e3ce508, v231
	v_rcp_f32_e32 v232, v230
	v_rcp_f32_e32 v233, v231
	v_lshlrev_b32_e32 v234, 16, v185
	v_and_b32_e32 v235, 0xffff0000, v185
	v_pk_mul_f32 v[232:233], v[232:233], v[234:235]
	v_pk_mul_f32 v[44:45], v[44:45], v[232:233]
	s_waitcnt vmcnt(8)
; __device__ __forceinline__ void unpack8(u32x4 w, f32x4& lo, f32x4& hi) { lo = (f32x4){bfl(w.x), bfh(w.x), bfl(w.y), bfh(w.y)}; hi = (f32x4){bfl(w.z), bfh(w.z), bfl(w.w), bfh(w.w)}; }
;     __device__ __forceinline__ void mid(f32x4 (&acc)[2][2][4][2], const Unit& u, int wr, int wc, int fr, int fq) const {
;     ...
;             for (int m = 0; m < 4; ++m) { const unsigned ro = base + (unsigned)((ai * HALF + m * 16) * D);
; #pragma unroll
;                 for (int bj = 0; bj < 2; ++bj) { const u32x4 aw = *(const u32x4*)(GA + ro + bj * HALF), bw = *(const u32x4*)(GB + ro + bj * HALF);
;                     f32x4 a0, a1, b0, b1; unpack8(aw, a0, a1); unpack8(bw, b0, b1);
; #pragma unroll
;                     for (int e = 0; e < 4; ++e) { acc[ai][bj][m][0][e] *= a0[e] * __builtin_amdgcn_rcpf(fmaxf(b0[e], 1e-20f)); acc[ai][bj][m][1][e] *= a1[e] * __builtin_amdgcn_rcpf(fmaxf(b1[e], 1e-20f)); } }
	v_lshlrev_b32_e32 v230, 16, v194
	v_and_b32_e32 v231, 0xffff0000, v194
	v_max_f32_e32 v230, v230, v230
	v_max_f32_e32 v231, v231, v231
	v_max_f32_e32 v230, 0x1e3ce508, v230
	v_max_f32_e32 v231, 0x1e3ce508, v231
	v_rcp_f32_e32 v232, v230
	v_rcp_f32_e32 v233, v231
	v_lshlrev_b32_e32 v234, 16, v190
	v_and_b32_e32 v235, 0xffff0000, v190
	v_pk_mul_f32 v[232:233], v[232:233], v[234:235]
	v_pk_mul_f32 v[38:39], v[38:39], v[232:233]
	v_lshlrev_b32_e32 v230, 16, v195
	v_and_b32_e32 v231, 0xffff0000, v195
	v_max_f32_e32 v230, v230, v230
	v_max_f32_e32 v231, v231, v231
	v_max_f32_e32 v230, 0x1e3ce508, v230
	v_max_f32_e32 v231, 0x1e3ce508, v231
	v_rcp_f32_e32 v232, v230
	v_rcp_f32_e32 v233, v231
	v_lshlrev_b32_e32 v234, 16, v191
	v_and_b32_e32 v235, 0xffff0000, v191
	v_pk_mul_f32 v[232:233], v[232:233], v[234:235]
	v_pk_mul_f32 v[40:41], v[40:41], v[232:233]
	v_lshlrev_b32_e32 v230, 16, v196
	v_and_b32_e32 v231, 0xffff0000, v196
	v_max_f32_e32 v230, v230, v230
	v_max_f32_e32 v231, v231, v231
	v_max_f32_e32 v230, 0x1e3ce508, v230
	v_max_f32_e32 v231, 0x1e3ce508, v231
	v_rcp_f32_e32 v232, v230
	v_rcp_f32_e32 v233, v231
	v_lshlrev_b32_e32 v234, 16, v192
	v_and_b32_e32 v235, 0xffff0000, v192
	v_pk_mul_f32 v[232:233], v[232:233], v[234:235]
	v_pk_mul_f32 v[34:35], v[34:35], v[232:233]
	v_lshlrev_b32_e32 v230, 16, v197
	v_and_b32_e32 v231, 0xffff0000, v197
	v_max_f32_e32 v230, v230, v230
	v_max_f32_e32 v231, v231, v231
	v_max_f32_e32 v230, 0x1e3ce508, v230
	v_max_f32_e32 v231, 0x1e3ce508, v231
	v_rcp_f32_e32 v232, v230
	v_rcp_f32_e32 v233, v231
	v_lshlrev_b32_e32 v234, 16, v193
	v_and_b32_e32 v235, 0xffff0000, v193
	v_pk_mul_f32 v[232:233], v[232:233], v[234:235]
	v_pk_mul_f32 v[36:37], v[36:37], v[232:233]
	s_waitcnt vmcnt(6)
	v_lshlrev_b32_e32 v230, 16, v202
	v_and_b32_e32 v231, 0xffff0000, v202
	v_max_f32_e32 v230, v230, v230
	v_max_f32_e32 v231, v231, v231
	v_max_f32_e32 v230, 0x1e3ce508, v230
	v_max_f32_e32 v231, 0x1e3ce508, v231
	v_rcp_f32_e32 v232, v230
	v_rcp_f32_e32 v233, v231
	v_lshlrev_b32_e32 v234, 16, v198
	v_and_b32_e32 v235, 0xffff0000, v198
	v_pk_mul_f32 v[232:233], v[232:233], v[234:235]
	v_pk_mul_f32 v[30:31], v[30:31], v[232:233]
	v_lshlrev_b32_e32 v230, 16, v203
	v_and_b32_e32 v231, 0xffff0000, v203
	v_max_f32_e32 v230, v230, v230
	v_max_f32_e32 v231, v231, v231
	v_max_f32_e32 v230, 0x1e3ce508, v230
	v_max_f32_e32 v231, 0x1e3ce508, v231
	v_rcp_f32_e32 v232, v230
	v_rcp_f32_e32 v233, v231
	v_lshlrev_b32_e32 v234, 16, v199
	v_and_b32_e32 v235, 0xffff0000, v199
	v_pk_mul_f32 v[232:233], v[232:233], v[234:235]
	v_pk_mul_f32 v[32:33], v[32:33], v[232:233]
	v_lshlrev_b32_e32 v230, 16, v204
	v_and_b32_e32 v231, 0xffff0000, v204
	v_max_f32_e32 v230, v230, v230
	v_max_f32_e32 v231, v231, v231
	v_max_f32_e32 v230, 0x1e3ce508, v230
	v_max_f32_e32 v231, 0x1e3ce508, v231
	v_rcp_f32_e32 v232, v230
	v_rcp_f32_e32 v233, v231
	v_lshlrev_b32_e32 v234, 16, v200
	v_and_b32_e32 v235, 0xffff0000, v200
	v_pk_mul_f32 v[232:233], v[232:233], v[234:235]
	v_pk_mul_f32 v[26:27], v[26:27], v[232:233]
	v_lshlrev_b32_e32 v230, 16, v205
	v_and_b32_e32 v231, 0xffff0000, v205
	v_max_f32_e32 v230, v230, v230
	v_max_f32_e32 v231, v231, v231
	v_max_f32_e32 v230, 0x1e3ce508, v230
	v_max_f32_e32 v231, 0x1e3ce508, v231
	v_rcp_f32_e32 v232, v230
	v_rcp_f32_e32 v233, v231
	v_lshlrev_b32_e32 v234, 16, v201
	v_and_b32_e32 v235, 0xffff0000, v201
	v_pk_mul_f32 v[232:233], v[232:233], v[234:235]
	v_pk_mul_f32 v[28:29], v[28:29], v[232:233]
	s_waitcnt vmcnt(4)
; __device__ __forceinline__ void unpack8(u32x4 w, f32x4& lo, f32x4& hi) { lo = (f32x4){bfl(w.x), bfh(w.x), bfl(w.y), bfh(w.y)}; hi = (f32x4){bfl(w.z), bfh(w.z), bfl(w.w), bfh(w.w)}; }
;     __device__ __forceinline__ void mid(f32x4 (&acc)[2][2][4][2], const Unit& u, int wr, int wc, int fr, int fq) const {
;     ...
;             for (int m = 0; m < 4; ++m) { const unsigned ro = base + (unsigned)((ai * HALF + m * 16) * D);
; #pragma unroll
;                 for (int bj = 0; bj < 2; ++bj) { const u32x4 aw = *(const u32x4*)(GA + ro + bj * HALF), bw = *(const u32x4*)(GB + ro + bj * HALF);
;                     f32x4 a0, a1, b0, b1; unpack8(aw, a0, a1); unpack8(bw, b0, b1);
; #pragma unroll
;                     for (int e = 0; e < 4; ++e) { acc[ai][bj][m][0][e] *= a0[e] * __builtin_amdgcn_rcpf(fmaxf(b0[e], 1e-20f)); acc[ai][bj][m][1][e] *= a1[e] * __builtin_amdgcn_rcpf(fmaxf(b1[e], 1e-20f)); } }
;                 asm volatile("" ::: "memory"); }
	v_lshlrev_b32_e32 v230, 16, v210
	v_and_b32_e32 v231, 0xffff0000, v210
	v_max_f32_e32 v230, v230, v230
	v_max_f32_e32 v231, v231, v231
	v_max_f32_e32 v230, 0x1e3ce508, v230
	v_max_f32_e32 v231, 0x1e3ce508, v231
	v_rcp_f32_e32 v232, v230
	v_rcp_f32_e32 v233, v231
	v_lshlrev_b32_e32 v234, 16, v206
	v_and_b32_e32 v235, 0xffff0000, v206
	v_pk_mul_f32 v[232:233], v[232:233], v[234:235]
	v_pk_mul_f32 v[22:23], v[22:23], v[232:233]
	v_lshlrev_b32_e32 v230, 16, v211
	v_and_b32_e32 v231, 0xffff0000, v211
	v_max_f32_e32 v230, v230, v230
	v_max_f32_e32 v231, v231, v231
	v_max_f32_e32 v230, 0x1e3ce508, v230
	v_max_f32_e32 v231, 0x1e3ce508, v231
	v_rcp_f32_e32 v232, v230
	v_rcp_f32_e32 v233, v231
	v_lshlrev_b32_e32 v234, 16, v207
	v_and_b32_e32 v235, 0xffff0000, v207
	v_pk_mul_f32 v[232:233], v[232:233], v[234:235]
	v_pk_mul_f32 v[24:25], v[24:25], v[232:233]
	v_lshlrev_b32_e32 v230, 16, v212
	v_and_b32_e32 v231, 0xffff0000, v212
	v_max_f32_e32 v230, v230, v230
	v_max_f32_e32 v231, v231, v231
	v_max_f32_e32 v230, 0x1e3ce508, v230
	v_max_f32_e32 v231, 0x1e3ce508, v231
	v_rcp_f32_e32 v232, v230
	v_rcp_f32_e32 v233, v231
	v_lshlrev_b32_e32 v234, 16, v208
	v_and_b32_e32 v235, 0xffff0000, v208
	v_pk_mul_f32 v[232:233], v[232:233], v[234:235]
	v_pk_mul_f32 v[18:19], v[18:19], v[232:233]
	v_lshlrev_b32_e32 v230, 16, v213
	v_and_b32_e32 v231, 0xffff0000, v213
	v_max_f32_e32 v230, v230, v230
	v_max_f32_e32 v231, v231, v231
	v_max_f32_e32 v230, 0x1e3ce508, v230
	v_max_f32_e32 v231, 0x1e3ce508, v231
	v_rcp_f32_e32 v232, v230
	v_rcp_f32_e32 v233, v231
	v_lshlrev_b32_e32 v234, 16, v209
	v_and_b32_e32 v235, 0xffff0000, v209
	v_pk_mul_f32 v[232:233], v[232:233], v[234:235]
	v_pk_mul_f32 v[20:21], v[20:21], v[232:233]
	s_waitcnt vmcnt(2)
	v_lshlrev_b32_e32 v230, 16, v218
	v_and_b32_e32 v231, 0xffff0000, v218
	v_max_f32_e32 v230, v230, v230
	v_max_f32_e32 v231, v231, v231
	v_max_f32_e32 v230, 0x1e3ce508, v230
	v_max_f32_e32 v231, 0x1e3ce508, v231
	v_rcp_f32_e32 v232, v230
	v_rcp_f32_e32 v233, v231
	v_lshlrev_b32_e32 v234, 16, v214
	v_and_b32_e32 v235, 0xffff0000, v214
	v_pk_mul_f32 v[232:233], v[232:233], v[234:235]
	v_pk_mul_f32 v[14:15], v[14:15], v[232:233]
	v_lshlrev_b32_e32 v230, 16, v219
	v_and_b32_e32 v231, 0xffff0000, v219
	v_max_f32_e32 v230, v230, v230
	v_max_f32_e32 v231, v231, v231
	v_max_f32_e32 v230, 0x1e3ce508, v230
	v_max_f32_e32 v231, 0x1e3ce508, v231
	v_rcp_f32_e32 v232, v230
	v_rcp_f32_e32 v233, v231
	v_lshlrev_b32_e32 v234, 16, v215
	v_and_b32_e32 v235, 0xffff0000, v215
	v_pk_mul_f32 v[232:233], v[232:233], v[234:235]
	v_pk_mul_f32 v[16:17], v[16:17], v[232:233]
	v_lshlrev_b32_e32 v230, 16, v220
	v_and_b32_e32 v231, 0xffff0000, v220
	v_max_f32_e32 v230, v230, v230
	v_max_f32_e32 v231, v231, v231
	v_max_f32_e32 v230, 0x1e3ce508, v230
	v_max_f32_e32 v231, 0x1e3ce508, v231
	v_rcp_f32_e32 v232, v230
	v_rcp_f32_e32 v233, v231
	v_lshlrev_b32_e32 v234, 16, v216
	v_and_b32_e32 v235, 0xffff0000, v216
	v_pk_mul_f32 v[232:233], v[232:233], v[234:235]
	v_pk_mul_f32 v[10:11], v[10:11], v[232:233]
	v_lshlrev_b32_e32 v230, 16, v221
	v_and_b32_e32 v231, 0xffff0000, v221
	v_max_f32_e32 v230, v230, v230
	v_max_f32_e32 v231, v231, v231
	v_max_f32_e32 v230, 0x1e3ce508, v230
	v_max_f32_e32 v231, 0x1e3ce508, v231
	v_rcp_f32_e32 v232, v230
	v_rcp_f32_e32 v233, v231
	v_lshlrev_b32_e32 v234, 16, v217
	v_and_b32_e32 v235, 0xffff0000, v217
	v_pk_mul_f32 v[232:233], v[232:233], v[234:235]
	v_pk_mul_f32 v[12:13], v[12:13], v[232:233]
	s_waitcnt vmcnt(0)
	v_lshlrev_b32_e32 v230, 16, v226
	v_and_b32_e32 v231, 0xffff0000, v226
	v_max_f32_e32 v230, v230, v230
	v_max_f32_e32 v231, v231, v231
	v_max_f32_e32 v230, 0x1e3ce508, v230
	v_max_f32_e32 v231, 0x1e3ce508, v231
	v_rcp_f32_e32 v232, v230
	v_rcp_f32_e32 v233, v231
	v_lshlrev_b32_e32 v234, 16, v222
	v_and_b32_e32 v235, 0xffff0000, v222
	v_pk_mul_f32 v[232:233], v[232:233], v[234:235]
	v_pk_mul_f32 v[6:7], v[6:7], v[232:233]
	v_lshlrev_b32_e32 v230, 16, v227
	v_and_b32_e32 v231, 0xffff0000, v227
	v_max_f32_e32 v230, v230, v230
	v_max_f32_e32 v231, v231, v231
	v_max_f32_e32 v230, 0x1e3ce508, v230
	v_max_f32_e32 v231, 0x1e3ce508, v231
	v_rcp_f32_e32 v232, v230
	v_rcp_f32_e32 v233, v231
	v_lshlrev_b32_e32 v234, 16, v223
	v_and_b32_e32 v235, 0xffff0000, v223
	v_pk_mul_f32 v[232:233], v[232:233], v[234:235]
	v_pk_mul_f32 v[8:9], v[8:9], v[232:233]
	v_lshlrev_b32_e32 v230, 16, v228
	v_and_b32_e32 v231, 0xffff0000, v228
	v_max_f32_e32 v230, v230, v230
	v_max_f32_e32 v231, v231, v231
	v_max_f32_e32 v230, 0x1e3ce508, v230
	v_max_f32_e32 v231, 0x1e3ce508, v231
	v_rcp_f32_e32 v232, v230
	v_rcp_f32_e32 v233, v231
	v_lshlrev_b32_e32 v234, 16, v224
	v_and_b32_e32 v235, 0xffff0000, v224
	v_pk_mul_f32 v[232:233], v[232:233], v[234:235]
	v_pk_mul_f32 v[2:3], v[2:3], v[232:233]
	v_lshlrev_b32_e32 v230, 16, v229
	v_and_b32_e32 v231, 0xffff0000, v229
	v_max_f32_e32 v230, v230, v230
	v_max_f32_e32 v231, v231, v231
	v_max_f32_e32 v230, 0x1e3ce508, v230
	v_max_f32_e32 v231, 0x1e3ce508, v231
	v_rcp_f32_e32 v232, v230
	v_rcp_f32_e32 v233, v231
	v_lshlrev_b32_e32 v234, 16, v225
	v_and_b32_e32 v235, 0xffff0000, v225
	v_pk_mul_f32 v[232:233], v[232:233], v[234:235]
	v_pk_mul_f32 v[4:5], v[4:5], v[232:233]
	s_branch .LBB0_1199
